# grid barrier: waiting workgroups invalidate their L1 right after arriving (overlapped with the wait) and leave on the per-XCD release word that the leader bumps after its own invalidate completed; no
# speedup vs baseline: 1.0113x; 1.0113x over previous
; __device__ __forceinline__ unsigned xb_ld(unsigned* p)              { return __hip_atomic_load(p, __ATOMIC_RELAXED, __HIP_MEMORY_SCOPE_AGENT); }
; __device__ __forceinline__ unsigned xb_add(unsigned* p, unsigned v) { return __hip_atomic_fetch_add(p, v, __ATOMIC_RELAXED, __HIP_MEMORY_SCOPE_AGENT); }
; #define XB_SPIN(cond, bar) do { unsigned _sp = 0; while (cond) { __builtin_amdgcn_s_sleep(1); \
;     if ((++_sp & 255u) == 0u) { if (xb_ld(&(bar)[XB_TMO])) break; if (_sp > XB_SPIN_CAP) { atomicAdd(&(bar)[XB_TMO], 1u); break; } } } } while (0)
; __device__ __forceinline__ void xcd_barrier(const XcdBarrier& b) {
;     ...
;         const unsigned old = xb_add(&bar[XB_XSUB(b.x)], 1u);
;         const unsigned gen = old / nloc;
;         if (old + 1u == (gen + 1u) * nloc) {
;             __builtin_amdgcn_fence(__ATOMIC_RELEASE, "agent");
;             asm volatile("s_waitcnt vmcnt(0)" ::: "memory");
;             const unsigned og = xb_add(&bar[XB_TOP], 1u);
;             const unsigned tg = og / nx;
;             if (og + 1u == (tg + 1u) * nx) xb_add(&bar[XB_TOPGEN], 1u);
;             else XB_SPIN(xb_ld(&bar[XB_TOPGEN]) == tg, bar);
;             __builtin_amdgcn_fence(__ATOMIC_ACQUIRE, "agent");
;             xb_add(&bar[XB_XGEN(b.x)], 1u);
;             asm volatile("s_waitcnt vmcnt(0)" ::: "memory");
;         } else {
;             XB_SPIN(xb_ld(&bar[XB_XGEN(b.x)]) == gen, bar);
.LBB0_125:
	s_or_b64 exec, exec, s[8:9]
	v_cvt_f32_u32_e32 v4, v2
	s_waitcnt vmcnt(0)
	v_readfirstlane_b32 s3, v3
	v_sub_u32_e32 v3, 0, v2
	v_rcp_iflag_f32_e32 v4, v4
	v_add_u32_e32 v5, s3, v1
	v_mul_f32_e32 v4, 0x4f7ffffe, v4
	v_cvt_u32_f32_e32 v4, v4
	v_mul_lo_u32 v1, v3, v4
	v_mul_hi_u32 v1, v4, v1
	v_add_u32_e32 v1, v4, v1
	v_mul_hi_u32 v1, v5, v1
	v_mul_lo_u32 v3, v1, v2
	v_sub_u32_e32 v3, v5, v3
	v_add_u32_e32 v4, 1, v1
	v_cmp_ge_u32_e32 vcc, v3, v2
	s_nop 1
	v_cndmask_b32_e32 v1, v1, v4, vcc
	v_sub_u32_e32 v4, v3, v2
	v_cndmask_b32_e32 v3, v3, v4, vcc
	v_add_u32_e32 v4, 1, v1
	v_cmp_ge_u32_e32 vcc, v3, v2
	v_add_u32_e32 v3, 1, v5
	s_nop 0
	v_cndmask_b32_e32 v1, v1, v4, vcc
	v_mul_lo_u32 v4, v2, v1
	v_add_u32_e32 v2, v4, v2
	v_cmp_ne_u32_e32 vcc, v3, v2
	s_and_saveexec_b64 s[6:7], vcc
	s_xor_b64 s[6:7], exec, s[6:7]
	s_cbranch_execz .LBB0_139
	s_waitcnt lgkmcnt(0)
	buffer_inv sc1
	v_mov_b32_e32 v0, 0x2000
	global_load_dword v0, v0, s[4:5] offset:1024 sc1
	s_add_u32 s12, s4, 0x2400
	s_addc_u32 s13, s5, 0
	s_waitcnt vmcnt(0)
	v_cmp_eq_u32_e32 vcc, v0, v1
	s_and_saveexec_b64 s[8:9], vcc
	s_cbranch_execz .LBB0_138
	s_add_u32 s10, s58, 0x2f80200
	s_addc_u32 s11, s59, 0
	s_mov_b32 s3, 1
	s_mov_b64 s[14:15], 0
	v_mov_b32_e32 v0, 0
	s_branch .LBB0_129

; __device__ __forceinline__ unsigned xb_ld(unsigned* p)              { return __hip_atomic_load(p, __ATOMIC_RELAXED, __HIP_MEMORY_SCOPE_AGENT); }
; #define XB_SPIN(cond, bar) do { unsigned _sp = 0; while (cond) { __builtin_amdgcn_s_sleep(1); \
;     if ((++_sp & 255u) == 0u) { if (xb_ld(&(bar)[XB_TMO])) break; if (_sp > XB_SPIN_CAP) { atomicAdd(&(bar)[XB_TMO], 1u); break; } } } } while (0)
; __device__ __forceinline__ void xcd_barrier(const XcdBarrier& b) {
;     ...
;             XB_SPIN(xb_ld(&bar[XB_XGEN(b.x)]) == gen, bar);
;             __builtin_amdgcn_fence(__ATOMIC_ACQUIRE, "agent");
;             asm volatile("s_waitcnt vmcnt(0)" ::: "memory");
.LBB0_138:
	s_or_b64 exec, exec, s[8:9]
	s_waitcnt vmcnt(0)
	s_waitcnt vmcnt(0)

; __device__ __forceinline__ unsigned xb_ld(unsigned* p)              { return __hip_atomic_load(p, __ATOMIC_RELAXED, __HIP_MEMORY_SCOPE_AGENT); }
; __device__ __forceinline__ unsigned xb_add(unsigned* p, unsigned v) { return __hip_atomic_fetch_add(p, v, __ATOMIC_RELAXED, __HIP_MEMORY_SCOPE_AGENT); }
; #define XB_SPIN(cond, bar) do { unsigned _sp = 0; while (cond) { __builtin_amdgcn_s_sleep(1); \
;     if ((++_sp & 255u) == 0u) { if (xb_ld(&(bar)[XB_TMO])) break; if (_sp > XB_SPIN_CAP) { atomicAdd(&(bar)[XB_TMO], 1u); break; } } } } while (0)
; __device__ __forceinline__ void xcd_barrier(const XcdBarrier& b) {
;     ...
;         if (old + 1u == (gen + 1u) * nloc) {
;             __builtin_amdgcn_fence(__ATOMIC_RELEASE, "agent");
;             asm volatile("s_waitcnt vmcnt(0)" ::: "memory");
;             const unsigned og = xb_add(&bar[XB_TOP], 1u);
;             const unsigned tg = og / nx;
;             if (og + 1u == (tg + 1u) * nx) xb_add(&bar[XB_TOPGEN], 1u);
;             else XB_SPIN(xb_ld(&bar[XB_TOPGEN]) == tg, bar);
;             __builtin_amdgcn_fence(__ATOMIC_ACQUIRE, "agent");
;             xb_add(&bar[XB_XGEN(b.x)], 1u);
;             asm volatile("s_waitcnt vmcnt(0)" ::: "memory");
.LBB0_156:
	s_or_b64 exec, exec, s[6:7]
	s_mov_b64 s[6:7], exec
	v_mbcnt_lo_u32_b32 v0, s6, 0
	v_mbcnt_hi_u32_b32 v0, s7, v0
	v_cmp_eq_u32_e32 vcc, 0, v0
	s_waitcnt vmcnt(0)
	buffer_inv sc1
	s_waitcnt vmcnt(0)
	s_and_saveexec_b64 s[8:9], vcc
	s_cbranch_execz .LBB0_158
	s_bcnt1_i32_b64 s3, s[6:7]
	v_mov_b32_e32 v0, 0x2000
	v_mov_b32_e32 v1, s3
	global_atomic_add v0, v1, s[4:5] offset:1024

; __device__ __forceinline__ unsigned xb_ld(unsigned* p)              { return __hip_atomic_load(p, __ATOMIC_RELAXED, __HIP_MEMORY_SCOPE_AGENT); }
; __device__ __forceinline__ unsigned xb_add(unsigned* p, unsigned v) { return __hip_atomic_fetch_add(p, v, __ATOMIC_RELAXED, __HIP_MEMORY_SCOPE_AGENT); }
; #define XB_SPIN(cond, bar) do { unsigned _sp = 0; while (cond) { __builtin_amdgcn_s_sleep(1); \
;     if ((++_sp & 255u) == 0u) { if (xb_ld(&(bar)[XB_TMO])) break; if (_sp > XB_SPIN_CAP) { atomicAdd(&(bar)[XB_TMO], 1u); break; } } } } while (0)
; __device__ __forceinline__ void xcd_barrier(const XcdBarrier& b) {
;     ...
;         const unsigned old = xb_add(&bar[XB_XSUB(b.x)], 1u);
;         const unsigned gen = old / nloc;
;         if (old + 1u == (gen + 1u) * nloc) {
;             __builtin_amdgcn_fence(__ATOMIC_RELEASE, "agent");
;             asm volatile("s_waitcnt vmcnt(0)" ::: "memory");
;             const unsigned og = xb_add(&bar[XB_TOP], 1u);
;             const unsigned tg = og / nx;
;             if (og + 1u == (tg + 1u) * nx) xb_add(&bar[XB_TOPGEN], 1u);
;             else XB_SPIN(xb_ld(&bar[XB_TOPGEN]) == tg, bar);
;             __builtin_amdgcn_fence(__ATOMIC_ACQUIRE, "agent");
;             xb_add(&bar[XB_XGEN(b.x)], 1u);
;             asm volatile("s_waitcnt vmcnt(0)" ::: "memory");
;         } else {
;             XB_SPIN(xb_ld(&bar[XB_XGEN(b.x)]) == gen, bar);
.LBB0_1043:
	s_or_b64 exec, exec, s[10:11]
	v_cvt_f32_u32_e32 v4, v2
	s_waitcnt vmcnt(0)
	v_readfirstlane_b32 s3, v3
	v_sub_u32_e32 v3, 0, v2
	v_rcp_iflag_f32_e32 v4, v4
	v_add_u32_e32 v5, s3, v1
	v_mul_f32_e32 v4, 0x4f7ffffe, v4
	v_cvt_u32_f32_e32 v4, v4
	v_mul_lo_u32 v1, v3, v4
	v_mul_hi_u32 v1, v4, v1
	v_add_u32_e32 v1, v4, v1
	v_mul_hi_u32 v1, v5, v1
	v_mul_lo_u32 v3, v1, v2
	v_sub_u32_e32 v3, v5, v3
	v_add_u32_e32 v4, 1, v1
	v_cmp_ge_u32_e32 vcc, v3, v2
	s_nop 1
	v_cndmask_b32_e32 v1, v1, v4, vcc
	v_sub_u32_e32 v4, v3, v2
	v_cndmask_b32_e32 v3, v3, v4, vcc
	v_add_u32_e32 v4, 1, v1
	v_cmp_ge_u32_e32 vcc, v3, v2
	v_add_u32_e32 v3, 1, v5
	s_nop 0
	v_cndmask_b32_e32 v1, v1, v4, vcc
	v_mul_lo_u32 v4, v2, v1
	v_add_u32_e32 v2, v4, v2
	v_cmp_ne_u32_e32 vcc, v3, v2
	s_and_saveexec_b64 s[6:7], vcc
	s_xor_b64 s[6:7], exec, s[6:7]
	s_cbranch_execz .LBB0_1057
	s_waitcnt lgkmcnt(0)
	buffer_inv sc1
	v_mov_b32_e32 v0, 0x2000
	global_load_dword v0, v0, s[4:5] offset:1024 sc1
	s_add_u32 s14, s4, 0x2400
	s_addc_u32 s15, s5, 0
	s_waitcnt vmcnt(0)
	v_cmp_eq_u32_e32 vcc, v0, v1
	s_and_saveexec_b64 s[10:11], vcc
	s_cbranch_execz .LBB0_1056
	s_add_u32 s12, s58, 0x2f80200
	s_addc_u32 s13, s59, 0
	s_mov_b32 s3, 1
	s_mov_b64 s[16:17], 0
	v_mov_b32_e32 v0, 0
	s_branch .LBB0_1047

; __device__ __forceinline__ unsigned xb_ld(unsigned* p)              { return __hip_atomic_load(p, __ATOMIC_RELAXED, __HIP_MEMORY_SCOPE_AGENT); }
; #define XB_SPIN(cond, bar) do { unsigned _sp = 0; while (cond) { __builtin_amdgcn_s_sleep(1); \
;     if ((++_sp & 255u) == 0u) { if (xb_ld(&(bar)[XB_TMO])) break; if (_sp > XB_SPIN_CAP) { atomicAdd(&(bar)[XB_TMO], 1u); break; } } } } while (0)
; __device__ __forceinline__ void xcd_barrier(const XcdBarrier& b) {
;     ...
;             XB_SPIN(xb_ld(&bar[XB_XGEN(b.x)]) == gen, bar);
;             __builtin_amdgcn_fence(__ATOMIC_ACQUIRE, "agent");
;             asm volatile("s_waitcnt vmcnt(0)" ::: "memory");
.LBB0_1056:
	s_or_b64 exec, exec, s[10:11]
	s_waitcnt vmcnt(0)
	s_waitcnt vmcnt(0)

; __device__ __forceinline__ unsigned xb_ld(unsigned* p)              { return __hip_atomic_load(p, __ATOMIC_RELAXED, __HIP_MEMORY_SCOPE_AGENT); }
; __device__ __forceinline__ unsigned xb_add(unsigned* p, unsigned v) { return __hip_atomic_fetch_add(p, v, __ATOMIC_RELAXED, __HIP_MEMORY_SCOPE_AGENT); }
; #define XB_SPIN(cond, bar) do { unsigned _sp = 0; while (cond) { __builtin_amdgcn_s_sleep(1); \
;     if ((++_sp & 255u) == 0u) { if (xb_ld(&(bar)[XB_TMO])) break; if (_sp > XB_SPIN_CAP) { atomicAdd(&(bar)[XB_TMO], 1u); break; } } } } while (0)
; __device__ __forceinline__ void xcd_barrier(const XcdBarrier& b) {
;     ...
;         if (old + 1u == (gen + 1u) * nloc) {
;             __builtin_amdgcn_fence(__ATOMIC_RELEASE, "agent");
;             asm volatile("s_waitcnt vmcnt(0)" ::: "memory");
;             const unsigned og = xb_add(&bar[XB_TOP], 1u);
;             const unsigned tg = og / nx;
;             if (og + 1u == (tg + 1u) * nx) xb_add(&bar[XB_TOPGEN], 1u);
;             else XB_SPIN(xb_ld(&bar[XB_TOPGEN]) == tg, bar);
;             __builtin_amdgcn_fence(__ATOMIC_ACQUIRE, "agent");
;             xb_add(&bar[XB_XGEN(b.x)], 1u);
;             asm volatile("s_waitcnt vmcnt(0)" ::: "memory");
.LBB0_1074:
	s_or_b64 exec, exec, s[6:7]
	s_mov_b64 s[6:7], exec
	v_mbcnt_lo_u32_b32 v0, s6, 0
	v_mbcnt_hi_u32_b32 v0, s7, v0
	v_cmp_eq_u32_e32 vcc, 0, v0
	s_waitcnt vmcnt(0)
	buffer_inv sc1
	s_waitcnt vmcnt(0)
	s_and_saveexec_b64 s[10:11], vcc
	s_cbranch_execz .LBB0_1076
	s_bcnt1_i32_b64 s3, s[6:7]
	v_mov_b32_e32 v0, 0x2000
	v_mov_b32_e32 v1, s3
	global_atomic_add v0, v1, s[4:5] offset:1024

; __device__ __forceinline__ unsigned xb_ld(unsigned* p)              { return __hip_atomic_load(p, __ATOMIC_RELAXED, __HIP_MEMORY_SCOPE_AGENT); }
; __device__ __forceinline__ unsigned xb_add(unsigned* p, unsigned v) { return __hip_atomic_fetch_add(p, v, __ATOMIC_RELAXED, __HIP_MEMORY_SCOPE_AGENT); }
; #define XB_SPIN(cond, bar) do { unsigned _sp = 0; while (cond) { __builtin_amdgcn_s_sleep(1); \
;     if ((++_sp & 255u) == 0u) { if (xb_ld(&(bar)[XB_TMO])) break; if (_sp > XB_SPIN_CAP) { atomicAdd(&(bar)[XB_TMO], 1u); break; } } } } while (0)
; __device__ __forceinline__ void xcd_barrier(const XcdBarrier& b) {
;     ...
;         const unsigned old = xb_add(&bar[XB_XSUB(b.x)], 1u);
;         const unsigned gen = old / nloc;
;         if (old + 1u == (gen + 1u) * nloc) {
;             __builtin_amdgcn_fence(__ATOMIC_RELEASE, "agent");
;             asm volatile("s_waitcnt vmcnt(0)" ::: "memory");
;             const unsigned og = xb_add(&bar[XB_TOP], 1u);
;             const unsigned tg = og / nx;
;             if (og + 1u == (tg + 1u) * nx) xb_add(&bar[XB_TOPGEN], 1u);
;             else XB_SPIN(xb_ld(&bar[XB_TOPGEN]) == tg, bar);
;             __builtin_amdgcn_fence(__ATOMIC_ACQUIRE, "agent");
;             xb_add(&bar[XB_XGEN(b.x)], 1u);
;             asm volatile("s_waitcnt vmcnt(0)" ::: "memory");
;         } else {
;             XB_SPIN(xb_ld(&bar[XB_XGEN(b.x)]) == gen, bar);
.LBB0_1188:
	s_or_b64 exec, exec, s[6:7]
	v_cvt_f32_u32_e32 v4, v2
	s_waitcnt vmcnt(0)
	v_readfirstlane_b32 s4, v3
	v_sub_u32_e32 v3, 0, v2
	v_rcp_iflag_f32_e32 v4, v4
	v_add_u32_e32 v5, s4, v1
	v_mul_f32_e32 v4, 0x4f7ffffe, v4
	v_cvt_u32_f32_e32 v4, v4
	v_mul_lo_u32 v1, v3, v4
	v_mul_hi_u32 v1, v4, v1
	v_add_u32_e32 v1, v4, v1
	v_mul_hi_u32 v1, v5, v1
	v_mul_lo_u32 v3, v1, v2
	v_sub_u32_e32 v3, v5, v3
	v_add_u32_e32 v4, 1, v1
	v_cmp_ge_u32_e32 vcc, v3, v2
	s_nop 1
	v_cndmask_b32_e32 v1, v1, v4, vcc
	v_sub_u32_e32 v4, v3, v2
	v_cndmask_b32_e32 v3, v3, v4, vcc
	v_add_u32_e32 v4, 1, v1
	v_cmp_ge_u32_e32 vcc, v3, v2
	v_add_u32_e32 v3, 1, v5
	s_nop 0
	v_cndmask_b32_e32 v1, v1, v4, vcc
	v_mul_lo_u32 v4, v2, v1
	v_add_u32_e32 v2, v4, v2
	v_cmp_ne_u32_e32 vcc, v3, v2
	s_and_saveexec_b64 s[4:5], vcc
	s_xor_b64 s[4:5], exec, s[4:5]
	s_cbranch_execz .LBB0_1202
	s_waitcnt lgkmcnt(0)
	buffer_inv sc1
	v_mov_b32_e32 v0, 0x2000
	global_load_dword v0, v0, s[2:3] offset:1024 sc1
	s_add_u32 s10, s2, 0x2400
	s_addc_u32 s11, s3, 0
	s_waitcnt vmcnt(0)
	v_cmp_eq_u32_e32 vcc, v0, v1
	s_and_saveexec_b64 s[6:7], vcc
	s_cbranch_execz .LBB0_1201
	s_add_u32 s8, s58, 0x2f80200
	s_addc_u32 s9, s59, 0
	s_mov_b32 s22, 1
	s_mov_b64 s[12:13], 0
	v_mov_b32_e32 v0, 0
	s_branch .LBB0_1192

; __device__ __forceinline__ unsigned xb_ld(unsigned* p)              { return __hip_atomic_load(p, __ATOMIC_RELAXED, __HIP_MEMORY_SCOPE_AGENT); }
; #define XB_SPIN(cond, bar) do { unsigned _sp = 0; while (cond) { __builtin_amdgcn_s_sleep(1); \
;     if ((++_sp & 255u) == 0u) { if (xb_ld(&(bar)[XB_TMO])) break; if (_sp > XB_SPIN_CAP) { atomicAdd(&(bar)[XB_TMO], 1u); break; } } } } while (0)
; __device__ __forceinline__ void xcd_barrier(const XcdBarrier& b) {
;     ...
;             XB_SPIN(xb_ld(&bar[XB_XGEN(b.x)]) == gen, bar);
;             __builtin_amdgcn_fence(__ATOMIC_ACQUIRE, "agent");
;             asm volatile("s_waitcnt vmcnt(0)" ::: "memory");
.LBB0_1201:
	s_or_b64 exec, exec, s[6:7]
	s_waitcnt vmcnt(0)
	s_waitcnt vmcnt(0)

; __device__ __forceinline__ unsigned xb_ld(unsigned* p)              { return __hip_atomic_load(p, __ATOMIC_RELAXED, __HIP_MEMORY_SCOPE_AGENT); }
; __device__ __forceinline__ unsigned xb_add(unsigned* p, unsigned v) { return __hip_atomic_fetch_add(p, v, __ATOMIC_RELAXED, __HIP_MEMORY_SCOPE_AGENT); }
; #define XB_SPIN(cond, bar) do { unsigned _sp = 0; while (cond) { __builtin_amdgcn_s_sleep(1); \
;     if ((++_sp & 255u) == 0u) { if (xb_ld(&(bar)[XB_TMO])) break; if (_sp > XB_SPIN_CAP) { atomicAdd(&(bar)[XB_TMO], 1u); break; } } } } while (0)
; __device__ __forceinline__ void xcd_barrier(const XcdBarrier& b) {
;     ...
;         if (old + 1u == (gen + 1u) * nloc) {
;             __builtin_amdgcn_fence(__ATOMIC_RELEASE, "agent");
;             asm volatile("s_waitcnt vmcnt(0)" ::: "memory");
;             const unsigned og = xb_add(&bar[XB_TOP], 1u);
;             const unsigned tg = og / nx;
;             if (og + 1u == (tg + 1u) * nx) xb_add(&bar[XB_TOPGEN], 1u);
;             else XB_SPIN(xb_ld(&bar[XB_TOPGEN]) == tg, bar);
;             __builtin_amdgcn_fence(__ATOMIC_ACQUIRE, "agent");
;             xb_add(&bar[XB_XGEN(b.x)], 1u);
;             asm volatile("s_waitcnt vmcnt(0)" ::: "memory");
.LBB0_1219:
	s_or_b64 exec, exec, s[4:5]
	s_mov_b64 s[4:5], exec
	v_mbcnt_lo_u32_b32 v0, s4, 0
	v_mbcnt_hi_u32_b32 v0, s5, v0
	v_cmp_eq_u32_e32 vcc, 0, v0
	s_waitcnt vmcnt(0)
	buffer_inv sc1
	s_waitcnt vmcnt(0)
	s_and_saveexec_b64 s[6:7], vcc
	s_cbranch_execz .LBB0_1221
	s_bcnt1_i32_b64 s4, s[4:5]
	v_mov_b32_e32 v0, 0x2000
	v_mov_b32_e32 v1, s4
	global_atomic_add v0, v1, s[2:3] offset:1024
